# v18 + M3 LRU-gate epilogue regenerated (packed add/mul/fma per 8 codes, same f32 ops and byte packing)
# speedup vs baseline: 1.0008x; 1.0008x over previous
; __device__ __forceinline__ float sigmoidf_fast(float x) { return __builtin_amdgcn_rcpf(1.0f + __builtin_amdgcn_exp2f(-1.44269504089f * x)); }
;     __device__ __forceinline__ void operator()(const f32x4 (&acc)[2][2][4][2], const Unit& u, int wr, int wc, int fr, int fq) const {
;         const int row0 = u.pm * BM + wr * 64 + fr, colt = wc * 32 + 8 * fq, ch = u.pn * HALF + colt;
;         float b[2][8];
; #pragma unroll
;         for (int k = 0; k < 8; ++k) { b[0][k] = ba[ch + k]; b[1][k] = bx[ch + k]; }
; #pragma unroll
;         for (int ai = 0; ai < 2; ++ai)
; #pragma unroll
;             for (int m = 0; m < 4; ++m) { unsigned char* rowp = Q + (size_t)(row0 + ai * HALF + m * 16) * 2048 + u.pn * BM + colt;
; #pragma unroll
;                 for (int bj = 0; bj < 2; ++bj) { const f32x4 v0 = acc[ai][bj][m][0], v1 = acc[ai][bj][m][1]; unsigned q[8];
; #pragma unroll
;                     for (int j = 0; j < 4; ++j) { q[j] = (unsigned)(255.0f * sigmoidf_fast(v0[j] + b[bj][j]) + 0.5f); q[4 + j] = (unsigned)(255.0f * sigmoidf_fast(v1[j] + b[bj][4 + j]) + 0.5f); }
;                     u32x2 w; w.x = q[0] | (q[1] << 8) | (q[2] << 16) | (q[3] << 24); w.y = q[4] | (q[5] << 8) | (q[6] << 16) | (q[7] << 24);
;                     *(u32x2*)(rowp + bj * HALF) = w; } }
.LBB0_1507:
	v_lshl_or_b32 v108, s67, 7, v154
	v_ashrrev_i32_e32 v109, 31, v108
	v_lshlrev_b64 v[108:109], 2, v[108:109]
	v_lshl_add_u64 v[110:111], s[42:43], 0, v[108:109]
	global_load_dwordx4 v[128:131], v[110:111], off
	global_load_dwordx4 v[124:127], v[110:111], off offset:16
	v_lshl_add_u64 v[108:109], s[44:45], 0, v[108:109]
	global_load_dwordx4 v[112:115], v[108:109], off
	s_nop 0
	global_load_dwordx4 v[108:111], v[108:109], off offset:16
	v_lshl_add_u32 v162, s56, 8, v186
	v_ashrrev_i32_e32 v163, 31, v162
	v_lshlrev_b64 v[160:161], 11, v[162:163]
	s_lshl_b32 s40, s67, 8
	s_ashr_i32 s41, s40, 31
	v_lshl_add_u64 v[160:161], s[26:27], 0, v[160:161]
	v_lshl_add_u64 v[160:161], v[160:161], 0, s[40:41]
	v_lshl_add_u64 v[160:161], v[160:161], 0, v[154:155]
	s_waitcnt vmcnt(0)
	s_mov_b32 s98, 0xbfb8aa3b
	s_mov_b32 s99, 0xbfb8aa3b
	v_pk_add_f32 v[190:191], v[144:145], v[128:129]
	v_pk_add_f32 v[192:193], v[146:147], v[130:131]
	v_pk_add_f32 v[194:195], v[140:141], v[124:125]
	v_pk_add_f32 v[196:197], v[142:143], v[126:127]
	v_pk_mul_f32 v[190:191], v[190:191], s[98:99]
	v_pk_mul_f32 v[192:193], v[192:193], s[98:99]
	v_pk_mul_f32 v[194:195], v[194:195], s[98:99]
	v_pk_mul_f32 v[196:197], v[196:197], s[98:99]
	v_exp_f32_e32 v190, v190
	v_exp_f32_e32 v191, v191
	v_exp_f32_e32 v192, v192
	v_exp_f32_e32 v193, v193
	v_exp_f32_e32 v194, v194
	v_exp_f32_e32 v195, v195
	v_exp_f32_e32 v196, v196
	v_exp_f32_e32 v197, v197
	v_pk_add_f32 v[190:191], v[190:191], 1.0 op_sel_hi:[1,0]
	v_pk_add_f32 v[192:193], v[192:193], 1.0 op_sel_hi:[1,0]
	v_pk_add_f32 v[194:195], v[194:195], 1.0 op_sel_hi:[1,0]
	v_pk_add_f32 v[196:197], v[196:197], 1.0 op_sel_hi:[1,0]
	v_rcp_f32_e32 v190, v190
	v_rcp_f32_e32 v191, v191
	v_rcp_f32_e32 v192, v192
	v_rcp_f32_e32 v193, v193
	v_rcp_f32_e32 v194, v194
	v_rcp_f32_e32 v195, v195
	v_rcp_f32_e32 v196, v196
	v_rcp_f32_e32 v197, v197
	v_pk_fma_f32 v[190:191], v[190:191], s[2:3], 0.5 op_sel_hi:[1,0,0]
	v_pk_fma_f32 v[192:193], v[192:193], s[2:3], 0.5 op_sel_hi:[1,0,0]
	v_pk_fma_f32 v[194:195], v[194:195], s[2:3], 0.5 op_sel_hi:[1,0,0]
	v_pk_fma_f32 v[196:197], v[196:197], s[2:3], 0.5 op_sel_hi:[1,0,0]
	v_cvt_u32_f32_e32 v190, v190
	v_cvt_u32_f32_e32 v191, v191
	v_cvt_u32_f32_sdwa v192, v192 dst_sel:WORD_1 dst_unused:UNUSED_PAD src0_sel:DWORD
	v_cvt_u32_f32_sdwa v193, v193 dst_sel:BYTE_3 dst_unused:UNUSED_PAD src0_sel:DWORD
	v_cvt_u32_f32_e32 v194, v194
	v_cvt_u32_f32_e32 v195, v195
	v_cvt_u32_f32_sdwa v196, v196 dst_sel:WORD_1 dst_unused:UNUSED_PAD src0_sel:DWORD
	v_cvt_u32_f32_sdwa v197, v197 dst_sel:BYTE_3 dst_unused:UNUSED_PAD src0_sel:DWORD
	v_lshl_or_b32 v190, v191, 8, v190
	v_lshl_or_b32 v194, v195, 8, v194
	v_or3_b32 v190, v190, v192, v193
	v_or3_b32 v191, v194, v196, v197
	global_store_dwordx2 v[160:161], v[190:191], off
	v_pk_add_f32 v[198:199], v[136:137], v[112:113]
	v_pk_add_f32 v[200:201], v[138:139], v[114:115]
	v_pk_add_f32 v[202:203], v[132:133], v[108:109]
	v_pk_add_f32 v[204:205], v[134:135], v[110:111]
	v_pk_mul_f32 v[198:199], v[198:199], s[98:99]
	v_pk_mul_f32 v[200:201], v[200:201], s[98:99]
	v_pk_mul_f32 v[202:203], v[202:203], s[98:99]
	v_pk_mul_f32 v[204:205], v[204:205], s[98:99]
	v_exp_f32_e32 v198, v198
	v_exp_f32_e32 v199, v199
	v_exp_f32_e32 v200, v200
	v_exp_f32_e32 v201, v201
	v_exp_f32_e32 v202, v202
	v_exp_f32_e32 v203, v203
	v_exp_f32_e32 v204, v204
	v_exp_f32_e32 v205, v205
	v_pk_add_f32 v[198:199], v[198:199], 1.0 op_sel_hi:[1,0]
	v_pk_add_f32 v[200:201], v[200:201], 1.0 op_sel_hi:[1,0]
	v_pk_add_f32 v[202:203], v[202:203], 1.0 op_sel_hi:[1,0]
	v_pk_add_f32 v[204:205], v[204:205], 1.0 op_sel_hi:[1,0]
	v_rcp_f32_e32 v198, v198
	v_rcp_f32_e32 v199, v199
	v_rcp_f32_e32 v200, v200
	v_rcp_f32_e32 v201, v201
	v_rcp_f32_e32 v202, v202
	v_rcp_f32_e32 v203, v203
	v_rcp_f32_e32 v204, v204
	v_rcp_f32_e32 v205, v205
	v_pk_fma_f32 v[198:199], v[198:199], s[2:3], 0.5 op_sel_hi:[1,0,0]
	v_pk_fma_f32 v[200:201], v[200:201], s[2:3], 0.5 op_sel_hi:[1,0,0]
	v_pk_fma_f32 v[202:203], v[202:203], s[2:3], 0.5 op_sel_hi:[1,0,0]
	v_pk_fma_f32 v[204:205], v[204:205], s[2:3], 0.5 op_sel_hi:[1,0,0]
	v_cvt_u32_f32_e32 v198, v198
	v_cvt_u32_f32_e32 v199, v199
	v_cvt_u32_f32_sdwa v200, v200 dst_sel:WORD_1 dst_unused:UNUSED_PAD src0_sel:DWORD
	v_cvt_u32_f32_sdwa v201, v201 dst_sel:BYTE_3 dst_unused:UNUSED_PAD src0_sel:DWORD
	v_cvt_u32_f32_e32 v202, v202
	v_cvt_u32_f32_e32 v203, v203
	v_cvt_u32_f32_sdwa v204, v204 dst_sel:WORD_1 dst_unused:UNUSED_PAD src0_sel:DWORD
	v_cvt_u32_f32_sdwa v205, v205 dst_sel:BYTE_3 dst_unused:UNUSED_PAD src0_sel:DWORD
	v_lshl_or_b32 v198, v199, 8, v198
	v_lshl_or_b32 v202, v203, 8, v202
	v_or3_b32 v198, v198, v200, v201
	v_or3_b32 v199, v202, v204, v205
	global_store_dwordx2 v[160:161], v[198:199], off offset:128
	v_pk_add_f32 v[190:191], v[120:121], v[128:129]
	v_pk_add_f32 v[192:193], v[122:123], v[130:131]
	v_pk_add_f32 v[194:195], v[116:117], v[124:125]
	v_pk_add_f32 v[196:197], v[118:119], v[126:127]
	v_pk_mul_f32 v[190:191], v[190:191], s[98:99]
	v_pk_mul_f32 v[192:193], v[192:193], s[98:99]
	v_pk_mul_f32 v[194:195], v[194:195], s[98:99]
	v_pk_mul_f32 v[196:197], v[196:197], s[98:99]
	v_exp_f32_e32 v190, v190
	v_exp_f32_e32 v191, v191
	v_exp_f32_e32 v192, v192
	v_exp_f32_e32 v193, v193
	v_exp_f32_e32 v194, v194
	v_exp_f32_e32 v195, v195
	v_exp_f32_e32 v196, v196
	v_exp_f32_e32 v197, v197
	v_pk_add_f32 v[190:191], v[190:191], 1.0 op_sel_hi:[1,0]
	v_pk_add_f32 v[192:193], v[192:193], 1.0 op_sel_hi:[1,0]
	v_pk_add_f32 v[194:195], v[194:195], 1.0 op_sel_hi:[1,0]
	v_pk_add_f32 v[196:197], v[196:197], 1.0 op_sel_hi:[1,0]
	v_rcp_f32_e32 v190, v190
	v_rcp_f32_e32 v191, v191
	v_rcp_f32_e32 v192, v192
; __device__ __forceinline__ float sigmoidf_fast(float x) { return __builtin_amdgcn_rcpf(1.0f + __builtin_amdgcn_exp2f(-1.44269504089f * x)); }
;     __device__ __forceinline__ void operator()(const f32x4 (&acc)[2][2][4][2], const Unit& u, int wr, int wc, int fr, int fq) const {
;     ...
;             for (int m = 0; m < 4; ++m) { unsigned char* rowp = Q + (size_t)(row0 + ai * HALF + m * 16) * 2048 + u.pn * BM + colt;
; #pragma unroll
;                 for (int bj = 0; bj < 2; ++bj) { const f32x4 v0 = acc[ai][bj][m][0], v1 = acc[ai][bj][m][1]; unsigned q[8];
; #pragma unroll
;                     for (int j = 0; j < 4; ++j) { q[j] = (unsigned)(255.0f * sigmoidf_fast(v0[j] + b[bj][j]) + 0.5f); q[4 + j] = (unsigned)(255.0f * sigmoidf_fast(v1[j] + b[bj][4 + j]) + 0.5f); }
;                     u32x2 w; w.x = q[0] | (q[1] << 8) | (q[2] << 16) | (q[3] << 24); w.y = q[4] | (q[5] << 8) | (q[6] << 16) | (q[7] << 24);
;                     *(u32x2*)(rowp + bj * HALF) = w; } }
	v_rcp_f32_e32 v193, v193
	v_rcp_f32_e32 v194, v194
	v_rcp_f32_e32 v195, v195
	v_rcp_f32_e32 v196, v196
	v_rcp_f32_e32 v197, v197
	v_pk_fma_f32 v[190:191], v[190:191], s[2:3], 0.5 op_sel_hi:[1,0,0]
	v_pk_fma_f32 v[192:193], v[192:193], s[2:3], 0.5 op_sel_hi:[1,0,0]
	v_pk_fma_f32 v[194:195], v[194:195], s[2:3], 0.5 op_sel_hi:[1,0,0]
	v_pk_fma_f32 v[196:197], v[196:197], s[2:3], 0.5 op_sel_hi:[1,0,0]
	v_cvt_u32_f32_e32 v190, v190
	v_cvt_u32_f32_e32 v191, v191
	v_cvt_u32_f32_sdwa v192, v192 dst_sel:WORD_1 dst_unused:UNUSED_PAD src0_sel:DWORD
	v_cvt_u32_f32_sdwa v193, v193 dst_sel:BYTE_3 dst_unused:UNUSED_PAD src0_sel:DWORD
	v_cvt_u32_f32_e32 v194, v194
	v_cvt_u32_f32_e32 v195, v195
	v_cvt_u32_f32_sdwa v196, v196 dst_sel:WORD_1 dst_unused:UNUSED_PAD src0_sel:DWORD
	v_cvt_u32_f32_sdwa v197, v197 dst_sel:BYTE_3 dst_unused:UNUSED_PAD src0_sel:DWORD
	s_mov_b64 s[40:41], 0x8000
	v_lshl_add_u64 v[206:207], v[160:161], 0, s[40:41]
	v_lshl_or_b32 v190, v191, 8, v190
	v_lshl_or_b32 v194, v195, 8, v194
	v_or3_b32 v190, v190, v192, v193
	v_or3_b32 v191, v194, v196, v197
	global_store_dwordx2 v[206:207], v[190:191], off
	v_pk_add_f32 v[198:199], v[104:105], v[112:113]
	v_pk_add_f32 v[200:201], v[106:107], v[114:115]
	v_pk_add_f32 v[202:203], v[100:101], v[108:109]
	v_pk_add_f32 v[204:205], v[102:103], v[110:111]
	v_pk_mul_f32 v[198:199], v[198:199], s[98:99]
	v_pk_mul_f32 v[200:201], v[200:201], s[98:99]
	v_pk_mul_f32 v[202:203], v[202:203], s[98:99]
	v_pk_mul_f32 v[204:205], v[204:205], s[98:99]
	v_exp_f32_e32 v198, v198
	v_exp_f32_e32 v199, v199
	v_exp_f32_e32 v200, v200
	v_exp_f32_e32 v201, v201
	v_exp_f32_e32 v202, v202
	v_exp_f32_e32 v203, v203
	v_exp_f32_e32 v204, v204
	v_exp_f32_e32 v205, v205
	v_pk_add_f32 v[198:199], v[198:199], 1.0 op_sel_hi:[1,0]
	v_pk_add_f32 v[200:201], v[200:201], 1.0 op_sel_hi:[1,0]
	v_pk_add_f32 v[202:203], v[202:203], 1.0 op_sel_hi:[1,0]
	v_pk_add_f32 v[204:205], v[204:205], 1.0 op_sel_hi:[1,0]
	v_rcp_f32_e32 v198, v198
	v_rcp_f32_e32 v199, v199
	v_rcp_f32_e32 v200, v200
	v_rcp_f32_e32 v201, v201
	v_rcp_f32_e32 v202, v202
	v_rcp_f32_e32 v203, v203
	v_rcp_f32_e32 v204, v204
	v_rcp_f32_e32 v205, v205
	v_pk_fma_f32 v[198:199], v[198:199], s[2:3], 0.5 op_sel_hi:[1,0,0]
	v_pk_fma_f32 v[200:201], v[200:201], s[2:3], 0.5 op_sel_hi:[1,0,0]
	v_pk_fma_f32 v[202:203], v[202:203], s[2:3], 0.5 op_sel_hi:[1,0,0]
	v_pk_fma_f32 v[204:205], v[204:205], s[2:3], 0.5 op_sel_hi:[1,0,0]
	v_cvt_u32_f32_e32 v198, v198
	v_cvt_u32_f32_e32 v199, v199
	v_cvt_u32_f32_sdwa v200, v200 dst_sel:WORD_1 dst_unused:UNUSED_PAD src0_sel:DWORD
	v_cvt_u32_f32_sdwa v201, v201 dst_sel:BYTE_3 dst_unused:UNUSED_PAD src0_sel:DWORD
	v_cvt_u32_f32_e32 v202, v202
	v_cvt_u32_f32_e32 v203, v203
	v_cvt_u32_f32_sdwa v204, v204 dst_sel:WORD_1 dst_unused:UNUSED_PAD src0_sel:DWORD
	v_cvt_u32_f32_sdwa v205, v205 dst_sel:BYTE_3 dst_unused:UNUSED_PAD src0_sel:DWORD
	v_lshl_or_b32 v198, v199, 8, v198
	v_lshl_or_b32 v202, v203, 8, v202
	v_or3_b32 v198, v198, v200, v201
	v_or3_b32 v199, v202, v204, v205
	global_store_dwordx2 v[206:207], v[198:199], off offset:128
	v_pk_add_f32 v[190:191], v[96:97], v[128:129]
	v_pk_add_f32 v[192:193], v[98:99], v[130:131]
	v_pk_add_f32 v[194:195], v[92:93], v[124:125]
	v_pk_add_f32 v[196:197], v[94:95], v[126:127]
	v_pk_mul_f32 v[190:191], v[190:191], s[98:99]
	v_pk_mul_f32 v[192:193], v[192:193], s[98:99]
	v_pk_mul_f32 v[194:195], v[194:195], s[98:99]
	v_pk_mul_f32 v[196:197], v[196:197], s[98:99]
	v_exp_f32_e32 v190, v190
	v_exp_f32_e32 v191, v191
	v_exp_f32_e32 v192, v192
	v_exp_f32_e32 v193, v193
	v_exp_f32_e32 v194, v194
	v_exp_f32_e32 v195, v195
	v_exp_f32_e32 v196, v196
	v_exp_f32_e32 v197, v197
	v_pk_add_f32 v[190:191], v[190:191], 1.0 op_sel_hi:[1,0]
	v_pk_add_f32 v[192:193], v[192:193], 1.0 op_sel_hi:[1,0]
	v_pk_add_f32 v[194:195], v[194:195], 1.0 op_sel_hi:[1,0]
	v_pk_add_f32 v[196:197], v[196:197], 1.0 op_sel_hi:[1,0]
	v_rcp_f32_e32 v190, v190
	v_rcp_f32_e32 v191, v191
	v_rcp_f32_e32 v192, v192
	v_rcp_f32_e32 v193, v193
	v_rcp_f32_e32 v194, v194
	v_rcp_f32_e32 v195, v195
	v_rcp_f32_e32 v196, v196
	v_rcp_f32_e32 v197, v197
	v_pk_fma_f32 v[190:191], v[190:191], s[2:3], 0.5 op_sel_hi:[1,0,0]
	v_pk_fma_f32 v[192:193], v[192:193], s[2:3], 0.5 op_sel_hi:[1,0,0]
	v_pk_fma_f32 v[194:195], v[194:195], s[2:3], 0.5 op_sel_hi:[1,0,0]
	v_pk_fma_f32 v[196:197], v[196:197], s[2:3], 0.5 op_sel_hi:[1,0,0]
	v_cvt_u32_f32_e32 v190, v190
	v_cvt_u32_f32_e32 v191, v191
	v_cvt_u32_f32_sdwa v192, v192 dst_sel:WORD_1 dst_unused:UNUSED_PAD src0_sel:DWORD
	v_cvt_u32_f32_sdwa v193, v193 dst_sel:BYTE_3 dst_unused:UNUSED_PAD src0_sel:DWORD
	v_cvt_u32_f32_e32 v194, v194
	v_cvt_u32_f32_e32 v195, v195
	v_cvt_u32_f32_sdwa v196, v196 dst_sel:WORD_1 dst_unused:UNUSED_PAD src0_sel:DWORD
	v_cvt_u32_f32_sdwa v197, v197 dst_sel:BYTE_3 dst_unused:UNUSED_PAD src0_sel:DWORD
	s_mov_b64 s[40:41], 0x10000
	v_lshl_add_u64 v[208:209], v[160:161], 0, s[40:41]
	v_lshl_or_b32 v190, v191, 8, v190
	v_lshl_or_b32 v194, v195, 8, v194
	v_or3_b32 v190, v190, v192, v193
	v_or3_b32 v191, v194, v196, v197
	global_store_dwordx2 v[208:209], v[190:191], off
	v_pk_add_f32 v[198:199], v[88:89], v[112:113]
	v_pk_add_f32 v[200:201], v[90:91], v[114:115]
	v_pk_add_f32 v[202:203], v[84:85], v[108:109]
	v_pk_add_f32 v[204:205], v[86:87], v[110:111]
	v_pk_mul_f32 v[198:199], v[198:199], s[98:99]
	v_pk_mul_f32 v[200:201], v[200:201], s[98:99]
	v_pk_mul_f32 v[202:203], v[202:203], s[98:99]
	v_pk_mul_f32 v[204:205], v[204:205], s[98:99]
	v_exp_f32_e32 v198, v198
	v_exp_f32_e32 v199, v199
	v_exp_f32_e32 v200, v200
	v_exp_f32_e32 v201, v201
	v_exp_f32_e32 v202, v202
	v_exp_f32_e32 v203, v203
	v_exp_f32_e32 v204, v204
; __device__ __forceinline__ float sigmoidf_fast(float x) { return __builtin_amdgcn_rcpf(1.0f + __builtin_amdgcn_exp2f(-1.44269504089f * x)); }
;     __device__ __forceinline__ void operator()(const f32x4 (&acc)[2][2][4][2], const Unit& u, int wr, int wc, int fr, int fq) const {
;     ...
;             for (int m = 0; m < 4; ++m) { unsigned char* rowp = Q + (size_t)(row0 + ai * HALF + m * 16) * 2048 + u.pn * BM + colt;
; #pragma unroll
;                 for (int bj = 0; bj < 2; ++bj) { const f32x4 v0 = acc[ai][bj][m][0], v1 = acc[ai][bj][m][1]; unsigned q[8];
; #pragma unroll
;                     for (int j = 0; j < 4; ++j) { q[j] = (unsigned)(255.0f * sigmoidf_fast(v0[j] + b[bj][j]) + 0.5f); q[4 + j] = (unsigned)(255.0f * sigmoidf_fast(v1[j] + b[bj][4 + j]) + 0.5f); }
;                     u32x2 w; w.x = q[0] | (q[1] << 8) | (q[2] << 16) | (q[3] << 24); w.y = q[4] | (q[5] << 8) | (q[6] << 16) | (q[7] << 24);
;                     *(u32x2*)(rowp + bj * HALF) = w; } }
	v_exp_f32_e32 v205, v205
	v_pk_add_f32 v[198:199], v[198:199], 1.0 op_sel_hi:[1,0]
	v_pk_add_f32 v[200:201], v[200:201], 1.0 op_sel_hi:[1,0]
	v_pk_add_f32 v[202:203], v[202:203], 1.0 op_sel_hi:[1,0]
	v_pk_add_f32 v[204:205], v[204:205], 1.0 op_sel_hi:[1,0]
	v_rcp_f32_e32 v198, v198
	v_rcp_f32_e32 v199, v199
	v_rcp_f32_e32 v200, v200
	v_rcp_f32_e32 v201, v201
	v_rcp_f32_e32 v202, v202
	v_rcp_f32_e32 v203, v203
	v_rcp_f32_e32 v204, v204
	v_rcp_f32_e32 v205, v205
	v_pk_fma_f32 v[198:199], v[198:199], s[2:3], 0.5 op_sel_hi:[1,0,0]
	v_pk_fma_f32 v[200:201], v[200:201], s[2:3], 0.5 op_sel_hi:[1,0,0]
	v_pk_fma_f32 v[202:203], v[202:203], s[2:3], 0.5 op_sel_hi:[1,0,0]
	v_pk_fma_f32 v[204:205], v[204:205], s[2:3], 0.5 op_sel_hi:[1,0,0]
	v_cvt_u32_f32_e32 v198, v198
	v_cvt_u32_f32_e32 v199, v199
	v_cvt_u32_f32_sdwa v200, v200 dst_sel:WORD_1 dst_unused:UNUSED_PAD src0_sel:DWORD
	v_cvt_u32_f32_sdwa v201, v201 dst_sel:BYTE_3 dst_unused:UNUSED_PAD src0_sel:DWORD
	v_cvt_u32_f32_e32 v202, v202
	v_cvt_u32_f32_e32 v203, v203
	v_cvt_u32_f32_sdwa v204, v204 dst_sel:WORD_1 dst_unused:UNUSED_PAD src0_sel:DWORD
	v_cvt_u32_f32_sdwa v205, v205 dst_sel:BYTE_3 dst_unused:UNUSED_PAD src0_sel:DWORD
	v_lshl_or_b32 v198, v199, 8, v198
	v_lshl_or_b32 v202, v203, 8, v202
	v_or3_b32 v198, v198, v200, v201
	v_or3_b32 v199, v202, v204, v205
	global_store_dwordx2 v[208:209], v[198:199], off offset:128
	v_pk_add_f32 v[190:191], v[80:81], v[128:129]
	v_pk_add_f32 v[192:193], v[82:83], v[130:131]
	v_pk_add_f32 v[194:195], v[76:77], v[124:125]
	v_pk_add_f32 v[196:197], v[78:79], v[126:127]
	v_pk_mul_f32 v[190:191], v[190:191], s[98:99]
	v_pk_mul_f32 v[192:193], v[192:193], s[98:99]
	v_pk_mul_f32 v[194:195], v[194:195], s[98:99]
	v_pk_mul_f32 v[196:197], v[196:197], s[98:99]
	v_exp_f32_e32 v190, v190
	v_exp_f32_e32 v191, v191
	v_exp_f32_e32 v192, v192
	v_exp_f32_e32 v193, v193
	v_exp_f32_e32 v194, v194
	v_exp_f32_e32 v195, v195
	v_exp_f32_e32 v196, v196
	v_exp_f32_e32 v197, v197
	v_pk_add_f32 v[190:191], v[190:191], 1.0 op_sel_hi:[1,0]
	v_pk_add_f32 v[192:193], v[192:193], 1.0 op_sel_hi:[1,0]
	v_pk_add_f32 v[194:195], v[194:195], 1.0 op_sel_hi:[1,0]
	v_pk_add_f32 v[196:197], v[196:197], 1.0 op_sel_hi:[1,0]
	v_rcp_f32_e32 v190, v190
	v_rcp_f32_e32 v191, v191
	v_rcp_f32_e32 v192, v192
	v_rcp_f32_e32 v193, v193
	v_rcp_f32_e32 v194, v194
	v_rcp_f32_e32 v195, v195
	v_rcp_f32_e32 v196, v196
	v_rcp_f32_e32 v197, v197
	v_pk_fma_f32 v[190:191], v[190:191], s[2:3], 0.5 op_sel_hi:[1,0,0]
	v_pk_fma_f32 v[192:193], v[192:193], s[2:3], 0.5 op_sel_hi:[1,0,0]
	v_pk_fma_f32 v[194:195], v[194:195], s[2:3], 0.5 op_sel_hi:[1,0,0]
	v_pk_fma_f32 v[196:197], v[196:197], s[2:3], 0.5 op_sel_hi:[1,0,0]
	v_cvt_u32_f32_e32 v190, v190
	v_cvt_u32_f32_e32 v191, v191
	v_cvt_u32_f32_sdwa v192, v192 dst_sel:WORD_1 dst_unused:UNUSED_PAD src0_sel:DWORD
	v_cvt_u32_f32_sdwa v193, v193 dst_sel:BYTE_3 dst_unused:UNUSED_PAD src0_sel:DWORD
	v_cvt_u32_f32_e32 v194, v194
	v_cvt_u32_f32_e32 v195, v195
	v_cvt_u32_f32_sdwa v196, v196 dst_sel:WORD_1 dst_unused:UNUSED_PAD src0_sel:DWORD
	v_cvt_u32_f32_sdwa v197, v197 dst_sel:BYTE_3 dst_unused:UNUSED_PAD src0_sel:DWORD
	s_mov_b64 s[40:41], 0x18000
	v_lshl_add_u64 v[206:207], v[160:161], 0, s[40:41]
	v_lshl_or_b32 v190, v191, 8, v190
	v_lshl_or_b32 v194, v195, 8, v194
	v_or3_b32 v190, v190, v192, v193
	v_or3_b32 v191, v194, v196, v197
	global_store_dwordx2 v[206:207], v[190:191], off
	v_pk_add_f32 v[198:199], v[72:73], v[112:113]
	v_pk_add_f32 v[200:201], v[74:75], v[114:115]
	v_pk_add_f32 v[202:203], v[68:69], v[108:109]
	v_pk_add_f32 v[204:205], v[70:71], v[110:111]
	v_pk_mul_f32 v[198:199], v[198:199], s[98:99]
	v_pk_mul_f32 v[200:201], v[200:201], s[98:99]
	v_pk_mul_f32 v[202:203], v[202:203], s[98:99]
	v_pk_mul_f32 v[204:205], v[204:205], s[98:99]
	v_exp_f32_e32 v198, v198
	v_exp_f32_e32 v199, v199
	v_exp_f32_e32 v200, v200
	v_exp_f32_e32 v201, v201
	v_exp_f32_e32 v202, v202
	v_exp_f32_e32 v203, v203
	v_exp_f32_e32 v204, v204
	v_exp_f32_e32 v205, v205
	v_pk_add_f32 v[198:199], v[198:199], 1.0 op_sel_hi:[1,0]
	v_pk_add_f32 v[200:201], v[200:201], 1.0 op_sel_hi:[1,0]
	v_pk_add_f32 v[202:203], v[202:203], 1.0 op_sel_hi:[1,0]
	v_pk_add_f32 v[204:205], v[204:205], 1.0 op_sel_hi:[1,0]
	v_rcp_f32_e32 v198, v198
	v_rcp_f32_e32 v199, v199
	v_rcp_f32_e32 v200, v200
	v_rcp_f32_e32 v201, v201
	v_rcp_f32_e32 v202, v202
	v_rcp_f32_e32 v203, v203
	v_rcp_f32_e32 v204, v204
	v_rcp_f32_e32 v205, v205
	v_pk_fma_f32 v[198:199], v[198:199], s[2:3], 0.5 op_sel_hi:[1,0,0]
	v_pk_fma_f32 v[200:201], v[200:201], s[2:3], 0.5 op_sel_hi:[1,0,0]
	v_pk_fma_f32 v[202:203], v[202:203], s[2:3], 0.5 op_sel_hi:[1,0,0]
	v_pk_fma_f32 v[204:205], v[204:205], s[2:3], 0.5 op_sel_hi:[1,0,0]
	v_cvt_u32_f32_e32 v198, v198
	v_cvt_u32_f32_e32 v199, v199
	v_cvt_u32_f32_sdwa v200, v200 dst_sel:WORD_1 dst_unused:UNUSED_PAD src0_sel:DWORD
	v_cvt_u32_f32_sdwa v201, v201 dst_sel:BYTE_3 dst_unused:UNUSED_PAD src0_sel:DWORD
	v_cvt_u32_f32_e32 v202, v202
	v_cvt_u32_f32_e32 v203, v203
	v_cvt_u32_f32_sdwa v204, v204 dst_sel:WORD_1 dst_unused:UNUSED_PAD src0_sel:DWORD
	v_cvt_u32_f32_sdwa v205, v205 dst_sel:BYTE_3 dst_unused:UNUSED_PAD src0_sel:DWORD
	v_lshl_or_b32 v198, v199, 8, v198
	v_lshl_or_b32 v202, v203, 8, v202
	v_or3_b32 v198, v198, v200, v201
	v_or3_b32 v199, v202, v204, v205
	global_store_dwordx2 v[206:207], v[198:199], off offset:128
	v_pk_add_f32 v[190:191], v[64:65], v[128:129]
	v_pk_add_f32 v[192:193], v[66:67], v[130:131]
	v_pk_add_f32 v[194:195], v[60:61], v[124:125]
	v_pk_add_f32 v[196:197], v[62:63], v[126:127]
	v_pk_mul_f32 v[190:191], v[190:191], s[98:99]
	v_pk_mul_f32 v[192:193], v[192:193], s[98:99]
; __device__ __forceinline__ float sigmoidf_fast(float x) { return __builtin_amdgcn_rcpf(1.0f + __builtin_amdgcn_exp2f(-1.44269504089f * x)); }
;     __device__ __forceinline__ void operator()(const f32x4 (&acc)[2][2][4][2], const Unit& u, int wr, int wc, int fr, int fq) const {
;     ...
;             for (int m = 0; m < 4; ++m) { unsigned char* rowp = Q + (size_t)(row0 + ai * HALF + m * 16) * 2048 + u.pn * BM + colt;
; #pragma unroll
;                 for (int bj = 0; bj < 2; ++bj) { const f32x4 v0 = acc[ai][bj][m][0], v1 = acc[ai][bj][m][1]; unsigned q[8];
; #pragma unroll
;                     for (int j = 0; j < 4; ++j) { q[j] = (unsigned)(255.0f * sigmoidf_fast(v0[j] + b[bj][j]) + 0.5f); q[4 + j] = (unsigned)(255.0f * sigmoidf_fast(v1[j] + b[bj][4 + j]) + 0.5f); }
;                     u32x2 w; w.x = q[0] | (q[1] << 8) | (q[2] << 16) | (q[3] << 24); w.y = q[4] | (q[5] << 8) | (q[6] << 16) | (q[7] << 24);
;                     *(u32x2*)(rowp + bj * HALF) = w; } }
	v_pk_mul_f32 v[194:195], v[194:195], s[98:99]
	v_pk_mul_f32 v[196:197], v[196:197], s[98:99]
	v_exp_f32_e32 v190, v190
	v_exp_f32_e32 v191, v191
	v_exp_f32_e32 v192, v192
	v_exp_f32_e32 v193, v193
	v_exp_f32_e32 v194, v194
	v_exp_f32_e32 v195, v195
	v_exp_f32_e32 v196, v196
	v_exp_f32_e32 v197, v197
	v_pk_add_f32 v[190:191], v[190:191], 1.0 op_sel_hi:[1,0]
	v_pk_add_f32 v[192:193], v[192:193], 1.0 op_sel_hi:[1,0]
	v_pk_add_f32 v[194:195], v[194:195], 1.0 op_sel_hi:[1,0]
	v_pk_add_f32 v[196:197], v[196:197], 1.0 op_sel_hi:[1,0]
	v_rcp_f32_e32 v190, v190
	v_rcp_f32_e32 v191, v191
	v_rcp_f32_e32 v192, v192
	v_rcp_f32_e32 v193, v193
	v_rcp_f32_e32 v194, v194
	v_rcp_f32_e32 v195, v195
	v_rcp_f32_e32 v196, v196
	v_rcp_f32_e32 v197, v197
	v_pk_fma_f32 v[190:191], v[190:191], s[2:3], 0.5 op_sel_hi:[1,0,0]
	v_pk_fma_f32 v[192:193], v[192:193], s[2:3], 0.5 op_sel_hi:[1,0,0]
	v_pk_fma_f32 v[194:195], v[194:195], s[2:3], 0.5 op_sel_hi:[1,0,0]
	v_pk_fma_f32 v[196:197], v[196:197], s[2:3], 0.5 op_sel_hi:[1,0,0]
	v_cvt_u32_f32_e32 v190, v190
	v_cvt_u32_f32_e32 v191, v191
	v_cvt_u32_f32_sdwa v192, v192 dst_sel:WORD_1 dst_unused:UNUSED_PAD src0_sel:DWORD
	v_cvt_u32_f32_sdwa v193, v193 dst_sel:BYTE_3 dst_unused:UNUSED_PAD src0_sel:DWORD
	v_cvt_u32_f32_e32 v194, v194
	v_cvt_u32_f32_e32 v195, v195
	v_cvt_u32_f32_sdwa v196, v196 dst_sel:WORD_1 dst_unused:UNUSED_PAD src0_sel:DWORD
	v_cvt_u32_f32_sdwa v197, v197 dst_sel:BYTE_3 dst_unused:UNUSED_PAD src0_sel:DWORD
	s_mov_b64 s[40:41], 0x40000
	v_lshl_add_u64 v[208:209], v[160:161], 0, s[40:41]
	v_lshl_or_b32 v190, v191, 8, v190
	v_lshl_or_b32 v194, v195, 8, v194
	v_or3_b32 v190, v190, v192, v193
	v_or3_b32 v191, v194, v196, v197
	global_store_dwordx2 v[208:209], v[190:191], off
	v_pk_add_f32 v[198:199], v[56:57], v[112:113]
	v_pk_add_f32 v[200:201], v[58:59], v[114:115]
	v_pk_add_f32 v[202:203], v[52:53], v[108:109]
	v_pk_add_f32 v[204:205], v[54:55], v[110:111]
	v_pk_mul_f32 v[198:199], v[198:199], s[98:99]
	v_pk_mul_f32 v[200:201], v[200:201], s[98:99]
	v_pk_mul_f32 v[202:203], v[202:203], s[98:99]
	v_pk_mul_f32 v[204:205], v[204:205], s[98:99]
	v_exp_f32_e32 v198, v198
	v_exp_f32_e32 v199, v199
	v_exp_f32_e32 v200, v200
	v_exp_f32_e32 v201, v201
	v_exp_f32_e32 v202, v202
	v_exp_f32_e32 v203, v203
	v_exp_f32_e32 v204, v204
	v_exp_f32_e32 v205, v205
	v_pk_add_f32 v[198:199], v[198:199], 1.0 op_sel_hi:[1,0]
	v_pk_add_f32 v[200:201], v[200:201], 1.0 op_sel_hi:[1,0]
	v_pk_add_f32 v[202:203], v[202:203], 1.0 op_sel_hi:[1,0]
	v_pk_add_f32 v[204:205], v[204:205], 1.0 op_sel_hi:[1,0]
	v_rcp_f32_e32 v198, v198
	v_rcp_f32_e32 v199, v199
	v_rcp_f32_e32 v200, v200
	v_rcp_f32_e32 v201, v201
	v_rcp_f32_e32 v202, v202
	v_rcp_f32_e32 v203, v203
	v_rcp_f32_e32 v204, v204
	v_rcp_f32_e32 v205, v205
	v_pk_fma_f32 v[198:199], v[198:199], s[2:3], 0.5 op_sel_hi:[1,0,0]
	v_pk_fma_f32 v[200:201], v[200:201], s[2:3], 0.5 op_sel_hi:[1,0,0]
	v_pk_fma_f32 v[202:203], v[202:203], s[2:3], 0.5 op_sel_hi:[1,0,0]
	v_pk_fma_f32 v[204:205], v[204:205], s[2:3], 0.5 op_sel_hi:[1,0,0]
	v_cvt_u32_f32_e32 v198, v198
	v_cvt_u32_f32_e32 v199, v199
	v_cvt_u32_f32_sdwa v200, v200 dst_sel:WORD_1 dst_unused:UNUSED_PAD src0_sel:DWORD
	v_cvt_u32_f32_sdwa v201, v201 dst_sel:BYTE_3 dst_unused:UNUSED_PAD src0_sel:DWORD
	v_cvt_u32_f32_e32 v202, v202
	v_cvt_u32_f32_e32 v203, v203
	v_cvt_u32_f32_sdwa v204, v204 dst_sel:WORD_1 dst_unused:UNUSED_PAD src0_sel:DWORD
	v_cvt_u32_f32_sdwa v205, v205 dst_sel:BYTE_3 dst_unused:UNUSED_PAD src0_sel:DWORD
	v_lshl_or_b32 v198, v199, 8, v198
	v_lshl_or_b32 v202, v203, 8, v202
	v_or3_b32 v198, v198, v200, v201
	v_or3_b32 v199, v202, v204, v205
	global_store_dwordx2 v[208:209], v[198:199], off offset:128
	v_pk_add_f32 v[190:191], v[48:49], v[128:129]
	v_pk_add_f32 v[192:193], v[50:51], v[130:131]
	v_pk_add_f32 v[194:195], v[44:45], v[124:125]
	v_pk_add_f32 v[196:197], v[46:47], v[126:127]
	v_pk_mul_f32 v[190:191], v[190:191], s[98:99]
	v_pk_mul_f32 v[192:193], v[192:193], s[98:99]
	v_pk_mul_f32 v[194:195], v[194:195], s[98:99]
	v_pk_mul_f32 v[196:197], v[196:197], s[98:99]
	v_exp_f32_e32 v190, v190
	v_exp_f32_e32 v191, v191
	v_exp_f32_e32 v192, v192
	v_exp_f32_e32 v193, v193
	v_exp_f32_e32 v194, v194
	v_exp_f32_e32 v195, v195
	v_exp_f32_e32 v196, v196
	v_exp_f32_e32 v197, v197
	v_pk_add_f32 v[190:191], v[190:191], 1.0 op_sel_hi:[1,0]
	v_pk_add_f32 v[192:193], v[192:193], 1.0 op_sel_hi:[1,0]
	v_pk_add_f32 v[194:195], v[194:195], 1.0 op_sel_hi:[1,0]
	v_pk_add_f32 v[196:197], v[196:197], 1.0 op_sel_hi:[1,0]
	v_rcp_f32_e32 v190, v190
	v_rcp_f32_e32 v191, v191
	v_rcp_f32_e32 v192, v192
	v_rcp_f32_e32 v193, v193
	v_rcp_f32_e32 v194, v194
	v_rcp_f32_e32 v195, v195
	v_rcp_f32_e32 v196, v196
	v_rcp_f32_e32 v197, v197
	v_pk_fma_f32 v[190:191], v[190:191], s[2:3], 0.5 op_sel_hi:[1,0,0]
	v_pk_fma_f32 v[192:193], v[192:193], s[2:3], 0.5 op_sel_hi:[1,0,0]
	v_pk_fma_f32 v[194:195], v[194:195], s[2:3], 0.5 op_sel_hi:[1,0,0]
	v_pk_fma_f32 v[196:197], v[196:197], s[2:3], 0.5 op_sel_hi:[1,0,0]
	v_cvt_u32_f32_e32 v190, v190
	v_cvt_u32_f32_e32 v191, v191
	v_cvt_u32_f32_sdwa v192, v192 dst_sel:WORD_1 dst_unused:UNUSED_PAD src0_sel:DWORD
	v_cvt_u32_f32_sdwa v193, v193 dst_sel:BYTE_3 dst_unused:UNUSED_PAD src0_sel:DWORD
	v_cvt_u32_f32_e32 v194, v194
	v_cvt_u32_f32_e32 v195, v195
	v_cvt_u32_f32_sdwa v196, v196 dst_sel:WORD_1 dst_unused:UNUSED_PAD src0_sel:DWORD
	v_cvt_u32_f32_sdwa v197, v197 dst_sel:BYTE_3 dst_unused:UNUSED_PAD src0_sel:DWORD
	s_mov_b64 s[40:41], 0x48000
	v_lshl_add_u64 v[206:207], v[160:161], 0, s[40:41]
	v_lshl_or_b32 v190, v191, 8, v190
	v_lshl_or_b32 v194, v195, 8, v194
	v_or3_b32 v190, v190, v192, v193
	v_or3_b32 v191, v194, v196, v197
; __device__ __forceinline__ float sigmoidf_fast(float x) { return __builtin_amdgcn_rcpf(1.0f + __builtin_amdgcn_exp2f(-1.44269504089f * x)); }
;     __device__ __forceinline__ void operator()(const f32x4 (&acc)[2][2][4][2], const Unit& u, int wr, int wc, int fr, int fq) const {
;     ...
;             for (int m = 0; m < 4; ++m) { unsigned char* rowp = Q + (size_t)(row0 + ai * HALF + m * 16) * 2048 + u.pn * BM + colt;
; #pragma unroll
;                 for (int bj = 0; bj < 2; ++bj) { const f32x4 v0 = acc[ai][bj][m][0], v1 = acc[ai][bj][m][1]; unsigned q[8];
; #pragma unroll
;                     for (int j = 0; j < 4; ++j) { q[j] = (unsigned)(255.0f * sigmoidf_fast(v0[j] + b[bj][j]) + 0.5f); q[4 + j] = (unsigned)(255.0f * sigmoidf_fast(v1[j] + b[bj][4 + j]) + 0.5f); }
;                     u32x2 w; w.x = q[0] | (q[1] << 8) | (q[2] << 16) | (q[3] << 24); w.y = q[4] | (q[5] << 8) | (q[6] << 16) | (q[7] << 24);
;                     *(u32x2*)(rowp + bj * HALF) = w; } }
	global_store_dwordx2 v[206:207], v[190:191], off
	v_pk_add_f32 v[198:199], v[40:41], v[112:113]
	v_pk_add_f32 v[200:201], v[42:43], v[114:115]
	v_pk_add_f32 v[202:203], v[36:37], v[108:109]
	v_pk_add_f32 v[204:205], v[38:39], v[110:111]
	v_pk_mul_f32 v[198:199], v[198:199], s[98:99]
	v_pk_mul_f32 v[200:201], v[200:201], s[98:99]
	v_pk_mul_f32 v[202:203], v[202:203], s[98:99]
	v_pk_mul_f32 v[204:205], v[204:205], s[98:99]
	v_exp_f32_e32 v198, v198
	v_exp_f32_e32 v199, v199
	v_exp_f32_e32 v200, v200
	v_exp_f32_e32 v201, v201
	v_exp_f32_e32 v202, v202
	v_exp_f32_e32 v203, v203
	v_exp_f32_e32 v204, v204
	v_exp_f32_e32 v205, v205
	v_pk_add_f32 v[198:199], v[198:199], 1.0 op_sel_hi:[1,0]
	v_pk_add_f32 v[200:201], v[200:201], 1.0 op_sel_hi:[1,0]
	v_pk_add_f32 v[202:203], v[202:203], 1.0 op_sel_hi:[1,0]
	v_pk_add_f32 v[204:205], v[204:205], 1.0 op_sel_hi:[1,0]
	v_rcp_f32_e32 v198, v198
	v_rcp_f32_e32 v199, v199
	v_rcp_f32_e32 v200, v200
	v_rcp_f32_e32 v201, v201
	v_rcp_f32_e32 v202, v202
	v_rcp_f32_e32 v203, v203
	v_rcp_f32_e32 v204, v204
	v_rcp_f32_e32 v205, v205
	v_pk_fma_f32 v[198:199], v[198:199], s[2:3], 0.5 op_sel_hi:[1,0,0]
	v_pk_fma_f32 v[200:201], v[200:201], s[2:3], 0.5 op_sel_hi:[1,0,0]
	v_pk_fma_f32 v[202:203], v[202:203], s[2:3], 0.5 op_sel_hi:[1,0,0]
	v_pk_fma_f32 v[204:205], v[204:205], s[2:3], 0.5 op_sel_hi:[1,0,0]
	v_cvt_u32_f32_e32 v198, v198
	v_cvt_u32_f32_e32 v199, v199
	v_cvt_u32_f32_sdwa v200, v200 dst_sel:WORD_1 dst_unused:UNUSED_PAD src0_sel:DWORD
	v_cvt_u32_f32_sdwa v201, v201 dst_sel:BYTE_3 dst_unused:UNUSED_PAD src0_sel:DWORD
	v_cvt_u32_f32_e32 v202, v202
	v_cvt_u32_f32_e32 v203, v203
	v_cvt_u32_f32_sdwa v204, v204 dst_sel:WORD_1 dst_unused:UNUSED_PAD src0_sel:DWORD
	v_cvt_u32_f32_sdwa v205, v205 dst_sel:BYTE_3 dst_unused:UNUSED_PAD src0_sel:DWORD
	v_lshl_or_b32 v198, v199, 8, v198
	v_lshl_or_b32 v202, v203, 8, v202
	v_or3_b32 v198, v198, v200, v201
	v_or3_b32 v199, v202, v204, v205
	global_store_dwordx2 v[206:207], v[198:199], off offset:128
	v_pk_add_f32 v[190:191], v[30:31], v[128:129]
	v_pk_add_f32 v[192:193], v[32:33], v[130:131]
	v_pk_add_f32 v[194:195], v[26:27], v[124:125]
	v_pk_add_f32 v[196:197], v[28:29], v[126:127]
	v_pk_mul_f32 v[190:191], v[190:191], s[98:99]
	v_pk_mul_f32 v[192:193], v[192:193], s[98:99]
	v_pk_mul_f32 v[194:195], v[194:195], s[98:99]
	v_pk_mul_f32 v[196:197], v[196:197], s[98:99]
	v_exp_f32_e32 v190, v190
	v_exp_f32_e32 v191, v191
	v_exp_f32_e32 v192, v192
	v_exp_f32_e32 v193, v193
	v_exp_f32_e32 v194, v194
	v_exp_f32_e32 v195, v195
	v_exp_f32_e32 v196, v196
	v_exp_f32_e32 v197, v197
	v_pk_add_f32 v[190:191], v[190:191], 1.0 op_sel_hi:[1,0]
	v_pk_add_f32 v[192:193], v[192:193], 1.0 op_sel_hi:[1,0]
	v_pk_add_f32 v[194:195], v[194:195], 1.0 op_sel_hi:[1,0]
	v_pk_add_f32 v[196:197], v[196:197], 1.0 op_sel_hi:[1,0]
	v_rcp_f32_e32 v190, v190
	v_rcp_f32_e32 v191, v191
	v_rcp_f32_e32 v192, v192
	v_rcp_f32_e32 v193, v193
	v_rcp_f32_e32 v194, v194
	v_rcp_f32_e32 v195, v195
	v_rcp_f32_e32 v196, v196
	v_rcp_f32_e32 v197, v197
	v_pk_fma_f32 v[190:191], v[190:191], s[2:3], 0.5 op_sel_hi:[1,0,0]
	v_pk_fma_f32 v[192:193], v[192:193], s[2:3], 0.5 op_sel_hi:[1,0,0]
	v_pk_fma_f32 v[194:195], v[194:195], s[2:3], 0.5 op_sel_hi:[1,0,0]
	v_pk_fma_f32 v[196:197], v[196:197], s[2:3], 0.5 op_sel_hi:[1,0,0]
	v_cvt_u32_f32_e32 v190, v190
	v_cvt_u32_f32_e32 v191, v191
	v_cvt_u32_f32_sdwa v192, v192 dst_sel:WORD_1 dst_unused:UNUSED_PAD src0_sel:DWORD
	v_cvt_u32_f32_sdwa v193, v193 dst_sel:BYTE_3 dst_unused:UNUSED_PAD src0_sel:DWORD
	v_cvt_u32_f32_e32 v194, v194
	v_cvt_u32_f32_e32 v195, v195
	v_cvt_u32_f32_sdwa v196, v196 dst_sel:WORD_1 dst_unused:UNUSED_PAD src0_sel:DWORD
	v_cvt_u32_f32_sdwa v197, v197 dst_sel:BYTE_3 dst_unused:UNUSED_PAD src0_sel:DWORD
	s_mov_b64 s[40:41], 0x50000
	v_lshl_add_u64 v[208:209], v[160:161], 0, s[40:41]
	v_lshl_or_b32 v190, v191, 8, v190
	v_lshl_or_b32 v194, v195, 8, v194
	v_or3_b32 v190, v190, v192, v193
	v_or3_b32 v191, v194, v196, v197
	global_store_dwordx2 v[208:209], v[190:191], off
	v_pk_add_f32 v[198:199], v[22:23], v[112:113]
	v_pk_add_f32 v[200:201], v[24:25], v[114:115]
	v_pk_add_f32 v[202:203], v[18:19], v[108:109]
	v_pk_add_f32 v[204:205], v[20:21], v[110:111]
	v_pk_mul_f32 v[198:199], v[198:199], s[98:99]
	v_pk_mul_f32 v[200:201], v[200:201], s[98:99]
	v_pk_mul_f32 v[202:203], v[202:203], s[98:99]
	v_pk_mul_f32 v[204:205], v[204:205], s[98:99]
	v_exp_f32_e32 v198, v198
	v_exp_f32_e32 v199, v199
	v_exp_f32_e32 v200, v200
	v_exp_f32_e32 v201, v201
	v_exp_f32_e32 v202, v202
	v_exp_f32_e32 v203, v203
	v_exp_f32_e32 v204, v204
	v_exp_f32_e32 v205, v205
	v_pk_add_f32 v[198:199], v[198:199], 1.0 op_sel_hi:[1,0]
	v_pk_add_f32 v[200:201], v[200:201], 1.0 op_sel_hi:[1,0]
	v_pk_add_f32 v[202:203], v[202:203], 1.0 op_sel_hi:[1,0]
	v_pk_add_f32 v[204:205], v[204:205], 1.0 op_sel_hi:[1,0]
	v_rcp_f32_e32 v198, v198
	v_rcp_f32_e32 v199, v199
	v_rcp_f32_e32 v200, v200
	v_rcp_f32_e32 v201, v201
	v_rcp_f32_e32 v202, v202
	v_rcp_f32_e32 v203, v203
	v_rcp_f32_e32 v204, v204
	v_rcp_f32_e32 v205, v205
; __device__ __forceinline__ float sigmoidf_fast(float x) { return __builtin_amdgcn_rcpf(1.0f + __builtin_amdgcn_exp2f(-1.44269504089f * x)); }
;     __device__ __forceinline__ void operator()(const f32x4 (&acc)[2][2][4][2], const Unit& u, int wr, int wc, int fr, int fq) const {
;     ...
;             for (int m = 0; m < 4; ++m) { unsigned char* rowp = Q + (size_t)(row0 + ai * HALF + m * 16) * 2048 + u.pn * BM + colt;
; #pragma unroll
;                 for (int bj = 0; bj < 2; ++bj) { const f32x4 v0 = acc[ai][bj][m][0], v1 = acc[ai][bj][m][1]; unsigned q[8];
; #pragma unroll
;                     for (int j = 0; j < 4; ++j) { q[j] = (unsigned)(255.0f * sigmoidf_fast(v0[j] + b[bj][j]) + 0.5f); q[4 + j] = (unsigned)(255.0f * sigmoidf_fast(v1[j] + b[bj][4 + j]) + 0.5f); }
;                     u32x2 w; w.x = q[0] | (q[1] << 8) | (q[2] << 16) | (q[3] << 24); w.y = q[4] | (q[5] << 8) | (q[6] << 16) | (q[7] << 24);
;                     *(u32x2*)(rowp + bj * HALF) = w; } }
	v_pk_fma_f32 v[198:199], v[198:199], s[2:3], 0.5 op_sel_hi:[1,0,0]
	v_pk_fma_f32 v[200:201], v[200:201], s[2:3], 0.5 op_sel_hi:[1,0,0]
	v_pk_fma_f32 v[202:203], v[202:203], s[2:3], 0.5 op_sel_hi:[1,0,0]
	v_pk_fma_f32 v[204:205], v[204:205], s[2:3], 0.5 op_sel_hi:[1,0,0]
	v_cvt_u32_f32_e32 v198, v198
	v_cvt_u32_f32_e32 v199, v199
	v_cvt_u32_f32_sdwa v200, v200 dst_sel:WORD_1 dst_unused:UNUSED_PAD src0_sel:DWORD
	v_cvt_u32_f32_sdwa v201, v201 dst_sel:BYTE_3 dst_unused:UNUSED_PAD src0_sel:DWORD
	v_cvt_u32_f32_e32 v202, v202
	v_cvt_u32_f32_e32 v203, v203
	v_cvt_u32_f32_sdwa v204, v204 dst_sel:WORD_1 dst_unused:UNUSED_PAD src0_sel:DWORD
	v_cvt_u32_f32_sdwa v205, v205 dst_sel:BYTE_3 dst_unused:UNUSED_PAD src0_sel:DWORD
	v_lshl_or_b32 v198, v199, 8, v198
	v_lshl_or_b32 v202, v203, 8, v202
	v_or3_b32 v198, v198, v200, v201
	v_or3_b32 v199, v202, v204, v205
	global_store_dwordx2 v[208:209], v[198:199], off offset:128
	v_pk_add_f32 v[190:191], v[14:15], v[128:129]
	v_pk_add_f32 v[192:193], v[16:17], v[130:131]
	v_pk_add_f32 v[194:195], v[10:11], v[124:125]
	v_pk_add_f32 v[196:197], v[12:13], v[126:127]
	v_pk_mul_f32 v[190:191], v[190:191], s[98:99]
	v_pk_mul_f32 v[192:193], v[192:193], s[98:99]
	v_pk_mul_f32 v[194:195], v[194:195], s[98:99]
	v_pk_mul_f32 v[196:197], v[196:197], s[98:99]
	v_exp_f32_e32 v190, v190
	v_exp_f32_e32 v191, v191
	v_exp_f32_e32 v192, v192
	v_exp_f32_e32 v193, v193
	v_exp_f32_e32 v194, v194
	v_exp_f32_e32 v195, v195
	v_exp_f32_e32 v196, v196
	v_exp_f32_e32 v197, v197
	v_pk_add_f32 v[190:191], v[190:191], 1.0 op_sel_hi:[1,0]
	v_pk_add_f32 v[192:193], v[192:193], 1.0 op_sel_hi:[1,0]
	v_pk_add_f32 v[194:195], v[194:195], 1.0 op_sel_hi:[1,0]
	v_pk_add_f32 v[196:197], v[196:197], 1.0 op_sel_hi:[1,0]
	v_rcp_f32_e32 v190, v190
	v_rcp_f32_e32 v191, v191
	v_rcp_f32_e32 v192, v192
	v_rcp_f32_e32 v193, v193
	v_rcp_f32_e32 v194, v194
	v_rcp_f32_e32 v195, v195
	v_rcp_f32_e32 v196, v196
	v_rcp_f32_e32 v197, v197
	v_pk_fma_f32 v[190:191], v[190:191], s[2:3], 0.5 op_sel_hi:[1,0,0]
	v_pk_fma_f32 v[192:193], v[192:193], s[2:3], 0.5 op_sel_hi:[1,0,0]
	v_pk_fma_f32 v[194:195], v[194:195], s[2:3], 0.5 op_sel_hi:[1,0,0]
	v_pk_fma_f32 v[196:197], v[196:197], s[2:3], 0.5 op_sel_hi:[1,0,0]
	v_cvt_u32_f32_e32 v190, v190
	v_cvt_u32_f32_e32 v191, v191
	v_cvt_u32_f32_sdwa v192, v192 dst_sel:WORD_1 dst_unused:UNUSED_PAD src0_sel:DWORD
	v_cvt_u32_f32_sdwa v193, v193 dst_sel:BYTE_3 dst_unused:UNUSED_PAD src0_sel:DWORD
	v_cvt_u32_f32_e32 v194, v194
	v_cvt_u32_f32_e32 v195, v195
	v_cvt_u32_f32_sdwa v196, v196 dst_sel:WORD_1 dst_unused:UNUSED_PAD src0_sel:DWORD
	v_cvt_u32_f32_sdwa v197, v197 dst_sel:BYTE_3 dst_unused:UNUSED_PAD src0_sel:DWORD
	s_mov_b64 s[40:41], 0x58000
	v_lshl_add_u64 v[206:207], v[160:161], 0, s[40:41]
	v_lshl_or_b32 v190, v191, 8, v190
	v_lshl_or_b32 v194, v195, 8, v194
	v_or3_b32 v190, v190, v192, v193
	v_or3_b32 v191, v194, v196, v197
	global_store_dwordx2 v[206:207], v[190:191], off
	v_pk_add_f32 v[198:199], v[6:7], v[112:113]
	v_pk_add_f32 v[200:201], v[8:9], v[114:115]
	v_pk_add_f32 v[202:203], v[2:3], v[108:109]
	v_pk_add_f32 v[204:205], v[4:5], v[110:111]
	v_pk_mul_f32 v[198:199], v[198:199], s[98:99]
	v_pk_mul_f32 v[200:201], v[200:201], s[98:99]
	v_pk_mul_f32 v[202:203], v[202:203], s[98:99]
	v_pk_mul_f32 v[204:205], v[204:205], s[98:99]
	v_exp_f32_e32 v198, v198
	v_exp_f32_e32 v199, v199
	v_exp_f32_e32 v200, v200
	v_exp_f32_e32 v201, v201
	v_exp_f32_e32 v202, v202
	v_exp_f32_e32 v203, v203
	v_exp_f32_e32 v204, v204
	v_exp_f32_e32 v205, v205
	v_pk_add_f32 v[198:199], v[198:199], 1.0 op_sel_hi:[1,0]
	v_pk_add_f32 v[200:201], v[200:201], 1.0 op_sel_hi:[1,0]
	v_pk_add_f32 v[202:203], v[202:203], 1.0 op_sel_hi:[1,0]
	v_pk_add_f32 v[204:205], v[204:205], 1.0 op_sel_hi:[1,0]
	v_rcp_f32_e32 v198, v198
	v_rcp_f32_e32 v199, v199
	v_rcp_f32_e32 v200, v200
	v_rcp_f32_e32 v201, v201
	v_rcp_f32_e32 v202, v202
	v_rcp_f32_e32 v203, v203
	v_rcp_f32_e32 v204, v204
	v_rcp_f32_e32 v205, v205
	v_pk_fma_f32 v[198:199], v[198:199], s[2:3], 0.5 op_sel_hi:[1,0,0]
	v_pk_fma_f32 v[200:201], v[200:201], s[2:3], 0.5 op_sel_hi:[1,0,0]
	v_pk_fma_f32 v[202:203], v[202:203], s[2:3], 0.5 op_sel_hi:[1,0,0]
	v_pk_fma_f32 v[204:205], v[204:205], s[2:3], 0.5 op_sel_hi:[1,0,0]
	v_cvt_u32_f32_e32 v198, v198
	v_cvt_u32_f32_e32 v199, v199
	v_cvt_u32_f32_sdwa v200, v200 dst_sel:WORD_1 dst_unused:UNUSED_PAD src0_sel:DWORD
	v_cvt_u32_f32_sdwa v201, v201 dst_sel:BYTE_3 dst_unused:UNUSED_PAD src0_sel:DWORD
	v_cvt_u32_f32_e32 v202, v202
	v_cvt_u32_f32_e32 v203, v203
	v_cvt_u32_f32_sdwa v204, v204 dst_sel:WORD_1 dst_unused:UNUSED_PAD src0_sel:DWORD
	v_cvt_u32_f32_sdwa v205, v205 dst_sel:BYTE_3 dst_unused:UNUSED_PAD src0_sel:DWORD
	v_lshl_or_b32 v198, v199, 8, v198
	v_lshl_or_b32 v202, v203, 8, v202
	v_or3_b32 v198, v198, v200, v201
	v_or3_b32 v199, v202, v204, v205
	s_and_b64 vcc, exec, s[38:39]
	s_mov_b64 s[38:39], -1
	global_store_dwordx2 v[206:207], v[198:199], off offset:128
	s_cbranch_vccnz .LBB0_1492
	s_andn2_b64 vcc, exec, s[36:37]
	s_cbranch_vccnz .LBB0_1491
	s_barrier
	s_branch .LBB0_1491
